# DF attention loop: second-half tile pointers via single 64-bit add with scalar constant, latch no longer clobbers s[6:7]
# baseline (speedup 1.0000x reference)
; DI void attn_item_df2(const bf16_t* Qb, const bf16_t* Kb, size_t mstride, const bf16_t* VTb, int q0, int nkt  , float cs,
;                       bf16_t* Orow, float lam, float outscale, const float* subw, char* smem) {
;     ...
;   for (int j = 1; j < nkt - 1; j += 2) {
;     D2_ITER(j, pB, pA);
;     D2_ITER(j + 1, pA, pB);
;   }
.LBB0_257:
	s_add_i32 s3, s3, 2
	s_mov_b64 s[24:25], 0x100
	s_mov_b64 s[98:99], 0x4000
	v_lshl_add_u64 v[182:183], v[182:183], 0, s[24:25]
	v_lshl_add_u64 v[184:185], v[184:185], 0, s[24:25]
	v_lshl_add_u64 v[186:187], v[186:187], 0, s[98:99]
	s_cmpk_lt_u32 s3, 0x81
	v_lshl_add_u64 v[188:189], v[188:189], 0, s[98:99]
	s_waitcnt lgkmcnt(0)
	s_barrier
	s_cbranch_scc0 .LBB0_262

.LBB0_260:
	s_mov_b64 s[98:99], 0x2000
	s_waitcnt lgkmcnt(0)
	v_lshl_add_u64 v[64:65], v[186:187], 0, s[98:99]
	s_barrier
	global_load_dwordx4 v[222:225], v[64:65], off
	v_lshl_add_u64 v[64:65], v[188:189], 0, s[98:99]
	v_mov_b32_e32 v191, v190
	global_load_dwordx4 v[154:157], v[64:65], off
	global_load_dwordx4 v[150:153], v[182:183], off offset:384
	global_load_dwordx4 v[146:149], v[184:185], off offset:384
	ds_read_b128 v[64:67], v219
	ds_read_b128 v[192:195], v219 offset:32
	ds_read_b128 v[68:71], v219 offset:4608
	ds_read_b128 v[196:199], v219 offset:4640
	ds_read_b128 v[226:229], v219 offset:64
	ds_read_b128 v[230:233], v219 offset:96
	ds_read_b128 v[234:237], v219 offset:4672
	ds_read_b128 v[238:241], v219 offset:4704
	s_waitcnt lgkmcnt(7)
	v_mfma_f32_32x32x16_bf16 v[80:95], v[64:67], v[142:145], 0
	v_fma_f32 v72, v112, s78, -v190
	v_fma_f32 v73, v113, s78, -v191
	v_fma_f32 v74, v114, s78, -v190
	v_fma_f32 v75, v115, s78, -v191
	v_exp_f32_e32 v72, v72
	v_exp_f32_e32 v73, v73
	v_exp_f32_e32 v74, v74
	v_exp_f32_e32 v75, v75
	v_pk_add_f32 v[64:65], v[72:73], 0 op_sel_hi:[1,0]
	v_cvt_pk_bf16_f32 v112, v72, v73
	v_pk_add_f32 v[114:115], v[74:75], v[64:65]
	v_cvt_pk_bf16_f32 v113, v74, v75
	s_waitcnt lgkmcnt(5)
	v_mfma_f32_32x32x16_bf16 v[64:79], v[68:71], v[142:145], 0
	v_mfma_f32_32x32x16_bf16 v[80:95], v[192:195], v[136:139], v[80:95]
	v_fma_f32 v116, v116, s78, -v190
	v_fma_f32 v117, v117, s78, -v191
	v_fma_f32 v118, v118, s78, -v190
	v_fma_f32 v119, v119, s78, -v191
	v_exp_f32_e32 v116, v116
	v_exp_f32_e32 v117, v117
	v_exp_f32_e32 v118, v118
	v_exp_f32_e32 v119, v119
	v_pk_add_f32 v[114:115], v[116:117], v[114:115]
	s_nop 0
	v_pk_add_f32 v[160:161], v[118:119], v[114:115]
	v_cvt_pk_bf16_f32 v114, v116, v117
	v_cvt_pk_bf16_f32 v115, v118, v119
	s_waitcnt lgkmcnt(4)
	v_mfma_f32_32x32x16_bf16 v[64:79], v[196:199], v[136:139], v[64:79]
	s_waitcnt lgkmcnt(3)
	v_mfma_f32_32x32x16_bf16 v[80:95], v[226:229], v[132:135], v[80:95]
	v_fma_f32 v116, v120, s78, -v190
	v_fma_f32 v117, v121, s78, -v191
	v_fma_f32 v118, v122, s78, -v190
	v_fma_f32 v119, v123, s78, -v191
	v_exp_f32_e32 v116, v116
	v_exp_f32_e32 v117, v117
	v_exp_f32_e32 v118, v118
	v_exp_f32_e32 v119, v119
	v_pk_add_f32 v[120:121], v[116:117], v[160:161]
	v_cvt_pk_bf16_f32 v116, v116, v117
	v_pk_add_f32 v[120:121], v[118:119], v[120:121]
	v_cvt_pk_bf16_f32 v117, v118, v119
	s_waitcnt lgkmcnt(1)
	v_mfma_f32_32x32x16_bf16 v[64:79], v[234:237], v[132:135], v[64:79]
	v_mfma_f32_32x32x16_bf16 v[80:95], v[230:233], v[128:131], v[80:95]
	v_fma_f32 v118, v124, s78, -v190
	v_fma_f32 v119, v125, s78, -v191
	v_fma_f32 v122, v126, s78, -v190
	v_fma_f32 v123, v127, s78, -v191
	v_exp_f32_e32 v118, v118
	v_exp_f32_e32 v119, v119
	v_exp_f32_e32 v122, v122
	v_exp_f32_e32 v123, v123
	v_pk_add_f32 v[120:121], v[118:119], v[120:121]
	v_cvt_pk_bf16_f32 v118, v118, v119
	v_pk_add_f32 v[160:161], v[122:123], v[120:121]
	v_cvt_pk_bf16_f32 v119, v122, v123
	s_waitcnt lgkmcnt(0)
	v_mfma_f32_32x32x16_bf16 v[64:79], v[238:241], v[128:131], v[64:79]
	s_mulk_i32 s24, 0x4800
	v_add_u32_e32 v159, s24, v218
	ds_read_b128 v[120:123], v159 offset:36864
	ds_read_b128 v[124:127], v159 offset:41472
	ds_read_b128 v[192:195], v159 offset:46080
	ds_read_b128 v[196:199], v159 offset:50688
	s_addk_i32 s25, 0x4800
	s_cmp_lg_u32 s30, 2
	s_cselect_b32 s24, s25, 0
	s_add_i32 s24, s24, 0
	v_add_u32_e32 v221, s24, v180
	v_add_u32_e32 v242, s24, v178
	ds_read_b128 v[226:229], v159 offset:36896
	ds_read_b128 v[230:233], v159 offset:41504
	ds_read_b128 v[234:237], v159 offset:46112
	ds_read_b128 v[238:241], v159 offset:50720
	s_waitcnt lgkmcnt(7)
	v_mfma_f32_32x32x16_bf16 v[16:31], v[120:123], v[112:115], v[16:31]
	v_fma_f32 v96, v96, s78, -v190
	v_fma_f32 v97, v97, s78, -v191
	v_fma_f32 v98, v98, s78, -v190
	v_fma_f32 v99, v99, s78, -v191
	v_exp_f32_e32 v96, v96
	v_exp_f32_e32 v97, v97
	v_exp_f32_e32 v98, v98
	v_exp_f32_e32 v99, v99
	v_pk_add_f32 v[120:121], v[96:97], v[160:161]
	v_cvt_pk_bf16_f32 v96, v96, v97
	v_pk_add_f32 v[120:121], v[98:99], v[120:121]
	v_cvt_pk_bf16_f32 v97, v98, v99
	s_waitcnt lgkmcnt(6)
	v_mfma_f32_32x32x16_bf16 v[48:63], v[124:127], v[112:115], v[48:63]
	s_waitcnt lgkmcnt(5)
	v_mfma_f32_32x32x16_bf16 v[32:47], v[192:195], v[112:115], v[32:47]
	v_fma_f32 v98, v100, s78, -v190
	v_fma_f32 v99, v101, s78, -v191
	v_fma_f32 v100, v102, s78, -v190
	v_fma_f32 v101, v103, s78, -v191
	v_exp_f32_e32 v98, v98
	v_exp_f32_e32 v99, v99
	v_exp_f32_e32 v100, v100
	v_exp_f32_e32 v101, v101
	v_pk_add_f32 v[102:103], v[98:99], v[120:121]
	v_cvt_pk_bf16_f32 v98, v98, v99
	v_pk_add_f32 v[160:161], v[100:101], v[102:103]
	v_cvt_pk_bf16_f32 v99, v100, v101
	s_waitcnt lgkmcnt(4)
	v_mfma_f32_32x32x16_bf16 v[0:15], v[196:199], v[112:115], v[0:15]
	s_waitcnt vmcnt(3)
	ds_write_b128 v217, v[222:225] offset:18432
	ds_read_b128 v[100:103], v159 offset:36928
	ds_read_b128 v[112:115], v159 offset:41536
	ds_read_b128 v[120:123], v159 offset:46144
	ds_read_b128 v[124:127], v159 offset:50752
	s_waitcnt lgkmcnt(8)
	v_mfma_f32_32x32x16_bf16 v[16:31], v[226:229], v[116:119], v[16:31]
	v_fma_f32 v104, v104, s78, -v190
	v_fma_f32 v105, v105, s78, -v191
	v_fma_f32 v106, v106, s78, -v190
	v_fma_f32 v107, v107, s78, -v191
	v_exp_f32_e32 v104, v104
	v_exp_f32_e32 v105, v105
	v_exp_f32_e32 v106, v106
	v_exp_f32_e32 v107, v107
	v_pk_add_f32 v[160:161], v[104:105], v[160:161]
	v_cvt_pk_bf16_f32 v104, v104, v105
	v_pk_add_f32 v[160:161], v[106:107], v[160:161]
	v_cvt_pk_bf16_f32 v105, v106, v107
	s_waitcnt lgkmcnt(7)
	v_mfma_f32_32x32x16_bf16 v[48:63], v[230:233], v[116:119], v[48:63]
	s_waitcnt lgkmcnt(6)
	v_mfma_f32_32x32x16_bf16 v[32:47], v[234:237], v[116:119], v[32:47]
	v_fma_f32 v106, v108, s78, -v190
	v_fma_f32 v107, v109, s78, -v191
	v_fma_f32 v108, v110, s78, -v190
	v_fma_f32 v109, v111, s78, -v191
	v_exp_f32_e32 v106, v106
	v_exp_f32_e32 v107, v107
	v_exp_f32_e32 v108, v108
	v_exp_f32_e32 v109, v109
	v_pk_add_f32 v[110:111], v[106:107], v[160:161]
	v_cvt_pk_bf16_f32 v106, v106, v107
	v_pk_add_f32 v[160:161], v[108:109], v[110:111]
	v_cvt_pk_bf16_f32 v107, v108, v109
	s_waitcnt lgkmcnt(5)
	v_mfma_f32_32x32x16_bf16 v[0:15], v[238:241], v[116:119], v[0:15]
	s_waitcnt vmcnt(2)
	ds_write_b128 v216, v[154:157] offset:18432
	ds_read_b128 v[108:111], v159 offset:36960
	ds_read_b128 v[116:119], v159 offset:41568
	ds_read_b128 v[154:157], v159 offset:46176
	ds_read_b128 v[190:193], v159 offset:50784
	s_waitcnt lgkmcnt(8)
	v_mfma_f32_32x32x16_bf16 v[16:31], v[100:103], v[96:99], v[16:31]
	s_mov_b32 s24, 0xf149f2ca
	v_max3_f32 v100, v80, s24, v81
	v_max3_f32 v100, v100, v82, v83
	v_max3_f32 v100, v100, v84, v85
	v_max3_f32 v100, v100, v86, v87
	s_waitcnt lgkmcnt(7)
	v_mfma_f32_32x32x16_bf16 v[48:63], v[112:115], v[96:99], v[48:63]
	s_waitcnt lgkmcnt(6)
	v_mfma_f32_32x32x16_bf16 v[32:47], v[120:123], v[96:99], v[32:47]
	v_max3_f32 v100, v100, v88, v89
	v_max3_f32 v100, v100, v90, v91
	v_max3_f32 v100, v100, v92, v93
	v_max3_f32 v100, v100, v94, v95
	s_waitcnt lgkmcnt(5)
	v_mfma_f32_32x32x16_bf16 v[0:15], v[124:127], v[96:99], v[0:15]
	s_waitcnt vmcnt(1)
	ds_write_b128 v242, v[150:153] offset:36864
	s_waitcnt lgkmcnt(4)
	v_mfma_f32_32x32x16_bf16 v[16:31], v[108:111], v[104:107], v[16:31]
	v_max3_f32 v96, v100, v64, v65
	v_max3_f32 v96, v96, v66, v67
	v_max3_f32 v96, v96, v68, v69
	v_max3_f32 v96, v96, v70, v71
	s_waitcnt lgkmcnt(3)
	v_mfma_f32_32x32x16_bf16 v[48:63], v[116:119], v[104:107], v[48:63]
	s_waitcnt lgkmcnt(2)
	v_mfma_f32_32x32x16_bf16 v[32:47], v[154:157], v[104:107], v[32:47]
	v_max3_f32 v96, v96, v72, v73
	v_max3_f32 v96, v96, v74, v75
	v_max3_f32 v96, v96, v76, v77
	v_max3_f32 v96, v96, v78, v79
	s_waitcnt lgkmcnt(1)
	v_mfma_f32_32x32x16_bf16 v[0:15], v[190:193], v[104:107], v[0:15]
	s_waitcnt vmcnt(0)
	ds_write_b128 v221, v[146:149] offset:36864
	v_add_f32_e32 v97, v160, v161
	v_add_f32_e32 v191, v158, v97
	v_mov_b32_e32 v97, v96
	s_nop 1
	v_permlane32_swap_b32_e32 v96, v97
	v_max_f32_e32 v96, v96, v97
	v_sub_f32_e32 v97, v96, v220
	v_mul_f32_e32 v97, 0x3e38aa3b, v97
	v_cmp_lt_f32_e32 vcc, s5, v97
	s_movk_i32 s27, 0x2000
	s_cbranch_vccz .LBB0_257
	v_max_f32_e32 v96, v96, v96
	v_max_f32_e32 v97, v220, v220
	v_max_f32_e32 v97, v97, v96
	v_sub_f32_e32 v96, v220, v97
	v_mul_f32_e32 v96, 0x3e38aa3b, v96
	v_exp_f32_e32 v96, v96
	v_mov_b32_e32 v220, v97
	v_pk_mul_f32 v[30:31], v[30:31], v[96:97] op_sel_hi:[1,0]
	v_pk_mul_f32 v[28:29], v[28:29], v[96:97] op_sel_hi:[1,0]
	v_pk_mul_f32 v[26:27], v[26:27], v[96:97] op_sel_hi:[1,0]
	v_pk_mul_f32 v[24:25], v[24:25], v[96:97] op_sel_hi:[1,0]
	v_pk_mul_f32 v[22:23], v[22:23], v[96:97] op_sel_hi:[1,0]
	v_pk_mul_f32 v[20:21], v[20:21], v[96:97] op_sel_hi:[1,0]
	v_pk_mul_f32 v[18:19], v[18:19], v[96:97] op_sel_hi:[1,0]
	v_pk_mul_f32 v[16:17], v[16:17], v[96:97] op_sel_hi:[1,0]
	v_pk_mul_f32 v[62:63], v[62:63], v[96:97] op_sel_hi:[1,0]
	v_pk_mul_f32 v[60:61], v[60:61], v[96:97] op_sel_hi:[1,0]
	v_pk_mul_f32 v[58:59], v[58:59], v[96:97] op_sel_hi:[1,0]
	v_pk_mul_f32 v[56:57], v[56:57], v[96:97] op_sel_hi:[1,0]
	v_pk_mul_f32 v[54:55], v[54:55], v[96:97] op_sel_hi:[1,0]
	v_pk_mul_f32 v[52:53], v[52:53], v[96:97] op_sel_hi:[1,0]
	v_pk_mul_f32 v[50:51], v[50:51], v[96:97] op_sel_hi:[1,0]
	v_pk_mul_f32 v[48:49], v[48:49], v[96:97] op_sel_hi:[1,0]
	v_pk_mul_f32 v[46:47], v[46:47], v[96:97] op_sel_hi:[1,0]
	v_pk_mul_f32 v[44:45], v[44:45], v[96:97] op_sel_hi:[1,0]
	v_pk_mul_f32 v[42:43], v[42:43], v[96:97] op_sel_hi:[1,0]
	v_pk_mul_f32 v[40:41], v[40:41], v[96:97] op_sel_hi:[1,0]
	v_pk_mul_f32 v[38:39], v[38:39], v[96:97] op_sel_hi:[1,0]
	v_pk_mul_f32 v[36:37], v[36:37], v[96:97] op_sel_hi:[1,0]
	v_pk_mul_f32 v[34:35], v[34:35], v[96:97] op_sel_hi:[1,0]
	v_pk_mul_f32 v[32:33], v[32:33], v[96:97] op_sel_hi:[1,0]
	v_pk_mul_f32 v[14:15], v[14:15], v[96:97] op_sel_hi:[1,0]
	v_pk_mul_f32 v[12:13], v[12:13], v[96:97] op_sel_hi:[1,0]
	v_pk_mul_f32 v[10:11], v[10:11], v[96:97] op_sel_hi:[1,0]
	v_pk_mul_f32 v[8:9], v[8:9], v[96:97] op_sel_hi:[1,0]
	v_pk_mul_f32 v[6:7], v[6:7], v[96:97] op_sel_hi:[1,0]
	v_pk_mul_f32 v[4:5], v[4:5], v[96:97] op_sel_hi:[1,0]
	v_pk_mul_f32 v[2:3], v[2:3], v[96:97] op_sel_hi:[1,0]
	v_pk_mul_f32 v[0:1], v[0:1], v[96:97] op_sel_hi:[1,0]
	v_mul_f32_e32 v191, v191, v96
	s_branch .LBB0_257
